# EpiRes X-path epilogue (res0+res1) hand-written: residual loads double-buffered across row groups, saddr addressing
# speedup vs baseline: 1.0020x; 1.0020x over previous
; __device__ __forceinline__ int modidx_tile(int pm) { return (pm % 9 == 0) ? 4 : pm / 9; }
;     __device__ __forceinline__ void operator()(EPI_ARGS) const {
;         const int row0 = u.pm * BM + wr * 64 + fr; const float* gv = gate + (size_t)modidx_tile(u.pm) * 12288;
; #pragma unroll
;         for (int bj = 0; bj < 2; ++bj) { const int col0 = u.pn * BM + bj * HALF + wc * 32 + 8 * fq; const f32x4 g0 = *(const f32x4*)(gv + col0), g1 = *(const f32x4*)(gv + col0 + 4);
; #pragma unroll
;             for (int ai = 0; ai < 2; ++ai) {
;                 if (u.atom) {
; #pragma unroll
;                     for (int m = 0; m < 4; ++m) { float* pp = PART + ((size_t)(u.kt0 / u.nkt) * 1024 + (u.pm / 9) * 256 + wr * 64 + fr + ai * HALF + m * 16) * DM + col0;
;                         *(f32x4*)pp = g0 * acc[ai][bj][m][0]; *(f32x4*)(pp + 4) = g1 * acc[ai][bj][m][1]; }
;                 } else { f32x4 x0[4], x1[4];
; #pragma unroll
;                     for (int m = 0; m < 4; ++m) { const int r_ = row0 + ai * HALF + m * 16; const float* p = (Xin ? Xin + (size_t)((r_ / SB) * SEQ + (r_ % SB) - CTXL) * DM : X + (size_t)r_ * DM) + col0; x0[m] = *(const f32x4*)p; x1[m] = *(const f32x4*)(p + 4); }
; #pragma unroll
;                     for (int m = 0; m < 4; ++m) { float* p = X + (size_t)(row0 + ai * HALF + m * 16) * DM + col0; *(f32x4*)p = x0[m] + g0 * acc[ai][bj][m][0]; *(f32x4*)(p + 4) = x1[m] + g1 * acc[ai][bj][m][1]; } }
;                 asm volatile("" ::: "memory"); } }
.LBB0_2010:
	s_andn2_b64 vcc, exec, s[80:81]
	s_cbranch_vccnz .Lmy_r0_old
	v_lshl_add_u32 v190, s78, 8, v170
	v_lshl_or_b32 v191, s6, 8, v216
	v_lshlrev_b32_e32 v238, 13, v190
	v_lshl_add_u32 v238, v191, 2, v238
	v_lshlrev_b32_e32 v239, 2, v191
	s_mul_hi_i32 s27, s78, 0x38e38e39
	s_lshr_b32 s30, s27, 31
	s_ashr_i32 s27, s27, 1
	s_add_i32 s27, s27, s30
	s_mul_i32 s30, s27, 9
	s_sub_i32 s30, s78, s30
	s_cmp_lg_u32 s30, 0
	s_cselect_b32 s30, s27, 4
	s_mul_i32 s30, s30, 0xc000
	s_add_u32 s4, s89, s30
	s_addc_u32 s5, s42, 0
	s_mov_b64 s[6:7], s[16:17]
	s_and_b64 vcc, exec, s[22:23]
	s_cbranch_vccz .Lmy_r0_nox
	s_add_i32 s27, s27, 1
	s_lshl_b32 s27, s27, 21
	s_sub_u32 s6, s12, s27
	s_subb_u32 s7, s13, 0
.Lmy_r0_nox:
	global_load_dwordx4 v[230:233], v239, s[4:5]
	global_load_dwordx4 v[234:237], v239, s[4:5] offset:16
	global_load_dwordx4 v[96:99], v238, s[6:7]
	global_load_dwordx4 v[100:103], v238, s[6:7] offset:16
	s_add_u32 s36, s6, 0x20000
	s_addc_u32 s37, s7, 0
	global_load_dwordx4 v[136:139], v238, s[36:37]
	global_load_dwordx4 v[140:143], v238, s[36:37] offset:16
	s_add_u32 s36, s6, 0x40000
	s_addc_u32 s37, s7, 0
	global_load_dwordx4 v[144:147], v238, s[36:37]
	global_load_dwordx4 v[148:151], v238, s[36:37] offset:16
	s_add_u32 s36, s6, 0x60000
	s_addc_u32 s37, s7, 0
	global_load_dwordx4 v[152:155], v238, s[36:37]
	global_load_dwordx4 v[156:159], v238, s[36:37] offset:16
	s_add_u32 s36, s6, 0x100000
	s_addc_u32 s37, s7, 0
	global_load_dwordx4 v[190:193], v238, s[36:37]
	global_load_dwordx4 v[194:197], v238, s[36:37] offset:16
	s_add_u32 s36, s6, 0x120000
	s_addc_u32 s37, s7, 0
	global_load_dwordx4 v[198:201], v238, s[36:37]
	global_load_dwordx4 v[202:205], v238, s[36:37] offset:16
	s_add_u32 s36, s6, 0x140000
	s_addc_u32 s37, s7, 0
	global_load_dwordx4 v[208:211], v238, s[36:37]
	global_load_dwordx4 v[218:221], v238, s[36:37] offset:16
	s_add_u32 s36, s6, 0x160000
	s_addc_u32 s37, s7, 0
	global_load_dwordx4 v[222:225], v238, s[36:37]
	global_load_dwordx4 v[226:229], v238, s[36:37] offset:16
	s_waitcnt vmcnt(8)
	v_fma_f32 v132, v230, v132, v96
	v_fma_f32 v133, v231, v133, v97
	v_fma_f32 v134, v232, v134, v98
	v_fma_f32 v135, v233, v135, v99
	v_fma_f32 v128, v234, v128, v100
	v_fma_f32 v129, v235, v129, v101
	v_fma_f32 v130, v236, v130, v102
	v_fma_f32 v131, v237, v131, v103
	v_fma_f32 v124, v230, v124, v136
	v_fma_f32 v125, v231, v125, v137
	v_fma_f32 v126, v232, v126, v138
	v_fma_f32 v127, v233, v127, v139
	v_fma_f32 v120, v234, v120, v140
	v_fma_f32 v121, v235, v121, v141
	v_fma_f32 v122, v236, v122, v142
	v_fma_f32 v123, v237, v123, v143
	v_fma_f32 v116, v230, v116, v144
	v_fma_f32 v117, v231, v117, v145
	v_fma_f32 v118, v232, v118, v146
	v_fma_f32 v119, v233, v119, v147
	v_fma_f32 v112, v234, v112, v148
	v_fma_f32 v113, v235, v113, v149
	v_fma_f32 v114, v236, v114, v150
	v_fma_f32 v115, v237, v115, v151
	v_fma_f32 v108, v230, v108, v152
	v_fma_f32 v109, v231, v109, v153
	v_fma_f32 v110, v232, v110, v154
	v_fma_f32 v111, v233, v111, v155
	v_fma_f32 v104, v234, v104, v156
	v_fma_f32 v105, v235, v105, v157
	v_fma_f32 v106, v236, v106, v158
	v_fma_f32 v107, v237, v107, v159
	global_store_dwordx4 v238, v[132:135], s[16:17]
	global_store_dwordx4 v238, v[128:131], s[16:17] offset:16
	s_add_u32 s64, s16, 0x20000
	s_addc_u32 s65, s17, 0
	global_store_dwordx4 v238, v[124:127], s[64:65]
	global_store_dwordx4 v238, v[120:123], s[64:65] offset:16
	s_add_u32 s64, s16, 0x40000
	s_addc_u32 s65, s17, 0
	global_store_dwordx4 v238, v[116:119], s[64:65]
	global_store_dwordx4 v238, v[112:115], s[64:65] offset:16
	s_add_u32 s64, s16, 0x60000
	s_addc_u32 s65, s17, 0
	global_store_dwordx4 v238, v[108:111], s[64:65]
	global_store_dwordx4 v238, v[104:107], s[64:65] offset:16
	global_load_dwordx4 v[96:99], v238, s[6:7] offset:512
	global_load_dwordx4 v[100:103], v238, s[6:7] offset:528
	s_add_u32 s36, s6, 0x20000
	s_addc_u32 s37, s7, 0
	global_load_dwordx4 v[136:139], v238, s[36:37] offset:512
	global_load_dwordx4 v[140:143], v238, s[36:37] offset:528
	s_add_u32 s36, s6, 0x40000
	s_addc_u32 s37, s7, 0
	global_load_dwordx4 v[144:147], v238, s[36:37] offset:512
	global_load_dwordx4 v[148:151], v238, s[36:37] offset:528
	s_add_u32 s36, s6, 0x60000
	s_addc_u32 s37, s7, 0
	global_load_dwordx4 v[152:155], v238, s[36:37] offset:512
	global_load_dwordx4 v[156:159], v238, s[36:37] offset:528
	global_load_dwordx4 v[132:135], v239, s[4:5] offset:512
	global_load_dwordx4 v[128:131], v239, s[4:5] offset:528
	s_waitcnt vmcnt(18)
;     __device__ __forceinline__ void operator()(EPI_ARGS) const {
;     ...
;         for (int bj = 0; bj < 2; ++bj) { const int col0 = u.pn * BM + bj * HALF + wc * 32 + 8 * fq; const f32x4 g0 = *(const f32x4*)(gv + col0), g1 = *(const f32x4*)(gv + col0 + 4);
; #pragma unroll
;             for (int ai = 0; ai < 2; ++ai) {
;                 if (u.atom) {
; #pragma unroll
;                     for (int m = 0; m < 4; ++m) { float* pp = PART + ((size_t)(u.kt0 / u.nkt) * 1024 + (u.pm / 9) * 256 + wr * 64 + fr + ai * HALF + m * 16) * DM + col0;
;                         *(f32x4*)pp = g0 * acc[ai][bj][m][0]; *(f32x4*)(pp + 4) = g1 * acc[ai][bj][m][1]; }
;                 } else { f32x4 x0[4], x1[4];
; #pragma unroll
;                     for (int m = 0; m < 4; ++m) { const int r_ = row0 + ai * HALF + m * 16; const float* p = (Xin ? Xin + (size_t)((r_ / SB) * SEQ + (r_ % SB) - CTXL) * DM : X + (size_t)r_ * DM) + col0; x0[m] = *(const f32x4*)p; x1[m] = *(const f32x4*)(p + 4); }
; #pragma unroll
;                     for (int m = 0; m < 4; ++m) { float* p = X + (size_t)(row0 + ai * HALF + m * 16) * DM + col0; *(f32x4*)p = x0[m] + g0 * acc[ai][bj][m][0]; *(f32x4*)(p + 4) = x1[m] + g1 * acc[ai][bj][m][1]; } }
;                 asm volatile("" ::: "memory"); } }
	v_fma_f32 v92, v230, v92, v190
	v_fma_f32 v93, v231, v93, v191
	v_fma_f32 v94, v232, v94, v192
	v_fma_f32 v95, v233, v95, v193
	v_fma_f32 v88, v234, v88, v194
	v_fma_f32 v89, v235, v89, v195
	v_fma_f32 v90, v236, v90, v196
	v_fma_f32 v91, v237, v91, v197
	v_fma_f32 v84, v230, v84, v198
	v_fma_f32 v85, v231, v85, v199
	v_fma_f32 v86, v232, v86, v200
	v_fma_f32 v87, v233, v87, v201
	v_fma_f32 v80, v234, v80, v202
	v_fma_f32 v81, v235, v81, v203
	v_fma_f32 v82, v236, v82, v204
	v_fma_f32 v83, v237, v83, v205
	v_fma_f32 v76, v230, v76, v208
	v_fma_f32 v77, v231, v77, v209
	v_fma_f32 v78, v232, v78, v210
	v_fma_f32 v79, v233, v79, v211
	v_fma_f32 v72, v234, v72, v218
	v_fma_f32 v73, v235, v73, v219
	v_fma_f32 v74, v236, v74, v220
	v_fma_f32 v75, v237, v75, v221
	v_fma_f32 v68, v230, v68, v222
	v_fma_f32 v69, v231, v69, v223
	v_fma_f32 v70, v232, v70, v224
	v_fma_f32 v71, v233, v71, v225
	v_fma_f32 v64, v234, v64, v226
	v_fma_f32 v65, v235, v65, v227
	v_fma_f32 v66, v236, v66, v228
	v_fma_f32 v67, v237, v67, v229
	s_add_u32 s64, s16, 0x100000
	s_addc_u32 s65, s17, 0
	global_store_dwordx4 v238, v[92:95], s[64:65]
	global_store_dwordx4 v238, v[88:91], s[64:65] offset:16
	s_add_u32 s64, s16, 0x120000
	s_addc_u32 s65, s17, 0
	global_store_dwordx4 v238, v[84:87], s[64:65]
	global_store_dwordx4 v238, v[80:83], s[64:65] offset:16
	s_add_u32 s64, s16, 0x140000
	s_addc_u32 s65, s17, 0
	global_store_dwordx4 v238, v[76:79], s[64:65]
	global_store_dwordx4 v238, v[72:75], s[64:65] offset:16
	s_add_u32 s64, s16, 0x160000
	s_addc_u32 s65, s17, 0
	global_store_dwordx4 v238, v[68:71], s[64:65]
	global_store_dwordx4 v238, v[64:67], s[64:65] offset:16
	s_add_u32 s36, s6, 0x100000
	s_addc_u32 s37, s7, 0
	global_load_dwordx4 v[190:193], v238, s[36:37] offset:512
	global_load_dwordx4 v[194:197], v238, s[36:37] offset:528
	s_add_u32 s36, s6, 0x120000
	s_addc_u32 s37, s7, 0
	global_load_dwordx4 v[198:201], v238, s[36:37] offset:512
	global_load_dwordx4 v[202:205], v238, s[36:37] offset:528
	s_add_u32 s36, s6, 0x140000
	s_addc_u32 s37, s7, 0
	global_load_dwordx4 v[208:211], v238, s[36:37] offset:512
	global_load_dwordx4 v[218:221], v238, s[36:37] offset:528
	s_add_u32 s36, s6, 0x160000
	s_addc_u32 s37, s7, 0
	global_load_dwordx4 v[222:225], v238, s[36:37] offset:512
	global_load_dwordx4 v[226:229], v238, s[36:37] offset:528
	s_waitcnt vmcnt(16)
	v_fma_f32 v60, v132, v60, v96
	v_fma_f32 v61, v133, v61, v97
	v_fma_f32 v62, v134, v62, v98
	v_fma_f32 v63, v135, v63, v99
	v_fma_f32 v56, v128, v56, v100
	v_fma_f32 v57, v129, v57, v101
	v_fma_f32 v58, v130, v58, v102
	v_fma_f32 v59, v131, v59, v103
	v_fma_f32 v52, v132, v52, v136
	v_fma_f32 v53, v133, v53, v137
	v_fma_f32 v54, v134, v54, v138
	v_fma_f32 v55, v135, v55, v139
	v_fma_f32 v48, v128, v48, v140
	v_fma_f32 v49, v129, v49, v141
	v_fma_f32 v50, v130, v50, v142
	v_fma_f32 v51, v131, v51, v143
	v_fma_f32 v44, v132, v44, v144
	v_fma_f32 v45, v133, v45, v145
	v_fma_f32 v46, v134, v46, v146
	v_fma_f32 v47, v135, v47, v147
	v_fma_f32 v40, v128, v40, v148
	v_fma_f32 v41, v129, v41, v149
	v_fma_f32 v42, v130, v42, v150
	v_fma_f32 v43, v131, v43, v151
	v_fma_f32 v36, v132, v36, v152
	v_fma_f32 v37, v133, v37, v153
	v_fma_f32 v38, v134, v38, v154
	v_fma_f32 v39, v135, v39, v155
	v_fma_f32 v32, v128, v32, v156
	v_fma_f32 v33, v129, v33, v157
	v_fma_f32 v34, v130, v34, v158
	v_fma_f32 v35, v131, v35, v159
	global_store_dwordx4 v238, v[60:63], s[16:17] offset:512
	global_store_dwordx4 v238, v[56:59], s[16:17] offset:528
	s_add_u32 s64, s16, 0x20000
	s_addc_u32 s65, s17, 0
	global_store_dwordx4 v238, v[52:55], s[64:65] offset:512
	global_store_dwordx4 v238, v[48:51], s[64:65] offset:528
	s_add_u32 s64, s16, 0x40000
	s_addc_u32 s65, s17, 0
	global_store_dwordx4 v238, v[44:47], s[64:65] offset:512
	global_store_dwordx4 v238, v[40:43], s[64:65] offset:528
	s_add_u32 s64, s16, 0x60000
	s_addc_u32 s65, s17, 0
	global_store_dwordx4 v238, v[36:39], s[64:65] offset:512
	global_store_dwordx4 v238, v[32:35], s[64:65] offset:528
	s_waitcnt vmcnt(8)
	v_fma_f32 v28, v132, v28, v190
	v_fma_f32 v29, v133, v29, v191
	v_fma_f32 v30, v134, v30, v192
	v_fma_f32 v31, v135, v31, v193
	v_fma_f32 v24, v128, v24, v194
	v_fma_f32 v25, v129, v25, v195
	v_fma_f32 v26, v130, v26, v196
	v_fma_f32 v27, v131, v27, v197
	v_fma_f32 v20, v132, v20, v198
	v_fma_f32 v21, v133, v21, v199
	v_fma_f32 v22, v134, v22, v200
	v_fma_f32 v23, v135, v23, v201
	v_fma_f32 v16, v128, v16, v202
	v_fma_f32 v17, v129, v17, v203
	v_fma_f32 v18, v130, v18, v204
	v_fma_f32 v19, v131, v19, v205
	v_fma_f32 v12, v132, v12, v208
	v_fma_f32 v13, v133, v13, v209
	v_fma_f32 v14, v134, v14, v210
	v_fma_f32 v15, v135, v15, v211
	v_fma_f32 v8, v128, v8, v218
	v_fma_f32 v9, v129, v9, v219
	v_fma_f32 v10, v130, v10, v220
	v_fma_f32 v11, v131, v11, v221
	v_fma_f32 v4, v132, v4, v222
	v_fma_f32 v5, v133, v5, v223
	v_fma_f32 v6, v134, v6, v224
	v_fma_f32 v7, v135, v7, v225
	v_fma_f32 v0, v128, v0, v226
	v_fma_f32 v1, v129, v1, v227
	v_fma_f32 v2, v130, v2, v228
	v_fma_f32 v3, v131, v3, v229
	s_add_u32 s64, s16, 0x100000
	s_addc_u32 s65, s17, 0
	global_store_dwordx4 v238, v[28:31], s[64:65] offset:512
	global_store_dwordx4 v238, v[24:27], s[64:65] offset:528
	s_add_u32 s64, s16, 0x120000
	s_addc_u32 s65, s17, 0
	global_store_dwordx4 v238, v[20:23], s[64:65] offset:512
	global_store_dwordx4 v238, v[16:19], s[64:65] offset:528
	s_add_u32 s64, s16, 0x140000
	s_addc_u32 s65, s17, 0
	global_store_dwordx4 v238, v[12:15], s[64:65] offset:512
	global_store_dwordx4 v238, v[8:11], s[64:65] offset:528
	s_add_u32 s64, s16, 0x160000
	s_addc_u32 s65, s17, 0
	global_store_dwordx4 v238, v[4:7], s[64:65] offset:512
	global_store_dwordx4 v238, v[0:3], s[64:65] offset:528
	s_branch .Lmy_r0_end

; #define PG8_BAR __builtin_amdgcn_s_barrier()
; template <class Epi, bool HAS_MID>
; __device__ __forceinline__ void gemm_phase(LAS unsigned char* lds, const Gemm g, const Sched& S, const Epi& E) {
;     ...
;         if (wr == 0) PG8_BAR;
;         E(acc, cur, wr, wc, fr, fq);
;         if (!has_next) break;
; #pragma unroll
;         for (int a = 0; a < 2; ++a)
; #pragma unroll
;             for (int b = 0; b < 2; ++b)
; #pragma unroll
;                 for (int m = 0; m < 4; ++m)
; #pragma unroll
;                     for (int n = 0; n < 2; ++n) acc[a][b][m][n] = (f32x4){0.f, 0.f, 0.f, 0.f};
;         cur = nxt; cA = nA; cB = nB; ++ui;
;         if (wr == 1) PG8_BAR;
;     }
.LBB0_2062:
	v_lshl_add_u64 v[0:1], v[190:191], 2, v[36:37]
	global_store_dwordx4 v[0:1], v[32:35], off offset:528
.Lmy_r0_end:
	s_and_b64 vcc, exec, s[2:3]
	s_mov_b64 s[2:3], -1
	s_cbranch_vccnz .LBB0_1991
	s_andn2_b64 vcc, exec, s[14:15]
	s_cbranch_vccnz .LBB0_1990
	s_barrier
	s_branch .LBB0_1990
.LBB0_2065:
	s_branch .LBB0_2019

; __device__ __forceinline__ int modidx_tile(int pm) { return (pm % 9 == 0) ? 4 : pm / 9; }
;     __device__ __forceinline__ void operator()(EPI_ARGS) const {
;         const int row0 = u.pm * BM + wr * 64 + fr; const float* gv = gate + (size_t)modidx_tile(u.pm) * 12288;
; #pragma unroll
;         for (int bj = 0; bj < 2; ++bj) { const int col0 = u.pn * BM + bj * HALF + wc * 32 + 8 * fq; const f32x4 g0 = *(const f32x4*)(gv + col0), g1 = *(const f32x4*)(gv + col0 + 4);
; #pragma unroll
;             for (int ai = 0; ai < 2; ++ai) {
;                 if (u.atom) {
; #pragma unroll
;                     for (int m = 0; m < 4; ++m) { float* pp = PART + ((size_t)(u.kt0 / u.nkt) * 1024 + (u.pm / 9) * 256 + wr * 64 + fr + ai * HALF + m * 16) * DM + col0;
;                         *(f32x4*)pp = g0 * acc[ai][bj][m][0]; *(f32x4*)(pp + 4) = g1 * acc[ai][bj][m][1]; }
;                 } else { f32x4 x0[4], x1[4];
; #pragma unroll
;                     for (int m = 0; m < 4; ++m) { const int r_ = row0 + ai * HALF + m * 16; const float* p = (Xin ? Xin + (size_t)((r_ / SB) * SEQ + (r_ % SB) - CTXL) * DM : X + (size_t)r_ * DM) + col0; x0[m] = *(const f32x4*)p; x1[m] = *(const f32x4*)(p + 4); }
; #pragma unroll
;                     for (int m = 0; m < 4; ++m) { float* p = X + (size_t)(row0 + ai * HALF + m * 16) * DM + col0; *(f32x4*)p = x0[m] + g0 * acc[ai][bj][m][0]; *(f32x4*)(p + 4) = x1[m] + g1 * acc[ai][bj][m][1]; } }
;                 asm volatile("" ::: "memory"); } }
.LBB0_3023:
	s_andn2_b64 vcc, exec, s[72:73]
	s_cbranch_vccnz .Lmy_r1_old
	v_lshl_add_u32 v194, s88, 8, v146
	v_lshl_or_b32 v195, s43, 8, v188
	v_lshlrev_b32_e32 v240, 13, v194
	v_lshl_add_u32 v240, v195, 2, v240
	v_lshlrev_b32_e32 v241, 2, v195
	s_mul_hi_i32 s27, s88, 0x38e38e39
	s_lshr_b32 s30, s27, 31
	s_ashr_i32 s27, s27, 1
	s_add_i32 s27, s27, s30
	s_mul_i32 s30, s27, 9
	s_sub_i32 s30, s88, s30
	s_cmp_lg_u32 s30, 0
	s_cselect_b32 s30, s27, 4
	s_mul_i32 s30, s30, 0xc000
	s_add_u32 s4, s59, s30
	s_addc_u32 s5, s60, 0
	global_load_dwordx4 v[232:235], v241, s[4:5]
	global_load_dwordx4 v[236:239], v241, s[4:5] offset:16
	global_load_dwordx4 v[128:131], v240, s[16:17]
	global_load_dwordx4 v[132:135], v240, s[16:17] offset:16
	s_add_u32 s36, s16, 0x20000
	s_addc_u32 s37, s17, 0
	global_load_dwordx4 v[136:139], v240, s[36:37]
	global_load_dwordx4 v[170:173], v240, s[36:37] offset:16
	s_add_u32 s36, s16, 0x40000
	s_addc_u32 s37, s17, 0
	global_load_dwordx4 v[174:177], v240, s[36:37]
	global_load_dwordx4 v[178:181], v240, s[36:37] offset:16
	s_add_u32 s36, s16, 0x60000
	s_addc_u32 s37, s17, 0
	global_load_dwordx4 v[182:185], v240, s[36:37]
	global_load_dwordx4 v[190:193], v240, s[36:37] offset:16
	s_add_u32 s36, s16, 0x100000
	s_addc_u32 s37, s17, 0
	global_load_dwordx4 v[194:197], v240, s[36:37]
	global_load_dwordx4 v[198:201], v240, s[36:37] offset:16
	s_add_u32 s36, s16, 0x120000
	s_addc_u32 s37, s17, 0
	global_load_dwordx4 v[202:205], v240, s[36:37]
	global_load_dwordx4 v[208:211], v240, s[36:37] offset:16
	s_add_u32 s36, s16, 0x140000
	s_addc_u32 s37, s17, 0
	global_load_dwordx4 v[216:219], v240, s[36:37]
	global_load_dwordx4 v[220:223], v240, s[36:37] offset:16
	s_add_u32 s36, s16, 0x160000
	s_addc_u32 s37, s17, 0
	global_load_dwordx4 v[224:227], v240, s[36:37]
	global_load_dwordx4 v[228:231], v240, s[36:37] offset:16
	s_waitcnt vmcnt(8)
	v_fma_f32 v124, v232, v124, v128
	v_fma_f32 v125, v233, v125, v129
	v_fma_f32 v126, v234, v126, v130
	v_fma_f32 v127, v235, v127, v131
	v_fma_f32 v120, v236, v120, v132
	v_fma_f32 v121, v237, v121, v133
	v_fma_f32 v122, v238, v122, v134
	v_fma_f32 v123, v239, v123, v135
	v_fma_f32 v116, v232, v116, v136
	v_fma_f32 v117, v233, v117, v137
	v_fma_f32 v118, v234, v118, v138
	v_fma_f32 v119, v235, v119, v139
	v_fma_f32 v112, v236, v112, v170
	v_fma_f32 v113, v237, v113, v171
	v_fma_f32 v114, v238, v114, v172
	v_fma_f32 v115, v239, v115, v173
	v_fma_f32 v108, v232, v108, v174
	v_fma_f32 v109, v233, v109, v175
	v_fma_f32 v110, v234, v110, v176
	v_fma_f32 v111, v235, v111, v177
	v_fma_f32 v104, v236, v104, v178
	v_fma_f32 v105, v237, v105, v179
	v_fma_f32 v106, v238, v106, v180
	v_fma_f32 v107, v239, v107, v181
	v_fma_f32 v100, v232, v100, v182
	v_fma_f32 v101, v233, v101, v183
	v_fma_f32 v102, v234, v102, v184
	v_fma_f32 v103, v235, v103, v185
	v_fma_f32 v96, v236, v96, v190
	v_fma_f32 v97, v237, v97, v191
	v_fma_f32 v98, v238, v98, v192
	v_fma_f32 v99, v239, v99, v193
	global_store_dwordx4 v240, v[124:127], s[16:17]
	global_store_dwordx4 v240, v[120:123], s[16:17] offset:16
	s_add_u32 s64, s16, 0x20000
	s_addc_u32 s65, s17, 0
	global_store_dwordx4 v240, v[116:119], s[64:65]
	global_store_dwordx4 v240, v[112:115], s[64:65] offset:16
	s_add_u32 s64, s16, 0x40000
	s_addc_u32 s65, s17, 0
	global_store_dwordx4 v240, v[108:111], s[64:65]
	global_store_dwordx4 v240, v[104:107], s[64:65] offset:16
	s_add_u32 s64, s16, 0x60000
	s_addc_u32 s65, s17, 0
	global_store_dwordx4 v240, v[100:103], s[64:65]
	global_store_dwordx4 v240, v[96:99], s[64:65] offset:16
	global_load_dwordx4 v[128:131], v240, s[16:17] offset:512
	global_load_dwordx4 v[132:135], v240, s[16:17] offset:528
	s_add_u32 s36, s16, 0x20000
	s_addc_u32 s37, s17, 0
	global_load_dwordx4 v[136:139], v240, s[36:37] offset:512
	global_load_dwordx4 v[170:173], v240, s[36:37] offset:528
	s_add_u32 s36, s16, 0x40000
	s_addc_u32 s37, s17, 0
	global_load_dwordx4 v[174:177], v240, s[36:37] offset:512
	global_load_dwordx4 v[178:181], v240, s[36:37] offset:528
	s_add_u32 s36, s16, 0x60000
	s_addc_u32 s37, s17, 0
	global_load_dwordx4 v[182:185], v240, s[36:37] offset:512
	global_load_dwordx4 v[190:193], v240, s[36:37] offset:528
	global_load_dwordx4 v[124:127], v241, s[4:5] offset:512
	global_load_dwordx4 v[120:123], v241, s[4:5] offset:528
	s_waitcnt vmcnt(18)
;     __device__ __forceinline__ void operator()(EPI_ARGS) const {
;     ...
;         for (int bj = 0; bj < 2; ++bj) { const int col0 = u.pn * BM + bj * HALF + wc * 32 + 8 * fq; const f32x4 g0 = *(const f32x4*)(gv + col0), g1 = *(const f32x4*)(gv + col0 + 4);
; #pragma unroll
;             for (int ai = 0; ai < 2; ++ai) {
;                 if (u.atom) {
; #pragma unroll
;                     for (int m = 0; m < 4; ++m) { float* pp = PART + ((size_t)(u.kt0 / u.nkt) * 1024 + (u.pm / 9) * 256 + wr * 64 + fr + ai * HALF + m * 16) * DM + col0;
;                         *(f32x4*)pp = g0 * acc[ai][bj][m][0]; *(f32x4*)(pp + 4) = g1 * acc[ai][bj][m][1]; }
;                 } else { f32x4 x0[4], x1[4];
; #pragma unroll
;                     for (int m = 0; m < 4; ++m) { const int r_ = row0 + ai * HALF + m * 16; const float* p = (Xin ? Xin + (size_t)((r_ / SB) * SEQ + (r_ % SB) - CTXL) * DM : X + (size_t)r_ * DM) + col0; x0[m] = *(const f32x4*)p; x1[m] = *(const f32x4*)(p + 4); }
; #pragma unroll
;                     for (int m = 0; m < 4; ++m) { float* p = X + (size_t)(row0 + ai * HALF + m * 16) * DM + col0; *(f32x4*)p = x0[m] + g0 * acc[ai][bj][m][0]; *(f32x4*)(p + 4) = x1[m] + g1 * acc[ai][bj][m][1]; } }
;                 asm volatile("" ::: "memory"); } }
	v_fma_f32 v92, v232, v92, v194
	v_fma_f32 v93, v233, v93, v195
	v_fma_f32 v94, v234, v94, v196
	v_fma_f32 v95, v235, v95, v197
	v_fma_f32 v88, v236, v88, v198
	v_fma_f32 v89, v237, v89, v199
	v_fma_f32 v90, v238, v90, v200
	v_fma_f32 v91, v239, v91, v201
	v_fma_f32 v84, v232, v84, v202
	v_fma_f32 v85, v233, v85, v203
	v_fma_f32 v86, v234, v86, v204
	v_fma_f32 v87, v235, v87, v205
	v_fma_f32 v80, v236, v80, v208
	v_fma_f32 v81, v237, v81, v209
	v_fma_f32 v82, v238, v82, v210
	v_fma_f32 v83, v239, v83, v211
	v_fma_f32 v76, v232, v76, v216
	v_fma_f32 v77, v233, v77, v217
	v_fma_f32 v78, v234, v78, v218
	v_fma_f32 v79, v235, v79, v219
	v_fma_f32 v72, v236, v72, v220
	v_fma_f32 v73, v237, v73, v221
	v_fma_f32 v74, v238, v74, v222
	v_fma_f32 v75, v239, v75, v223
	v_fma_f32 v68, v232, v68, v224
	v_fma_f32 v69, v233, v69, v225
	v_fma_f32 v70, v234, v70, v226
	v_fma_f32 v71, v235, v71, v227
	v_fma_f32 v64, v236, v64, v228
	v_fma_f32 v65, v237, v65, v229
	v_fma_f32 v66, v238, v66, v230
	v_fma_f32 v67, v239, v67, v231
	s_add_u32 s64, s16, 0x100000
	s_addc_u32 s65, s17, 0
	global_store_dwordx4 v240, v[92:95], s[64:65]
	global_store_dwordx4 v240, v[88:91], s[64:65] offset:16
	s_add_u32 s64, s16, 0x120000
	s_addc_u32 s65, s17, 0
	global_store_dwordx4 v240, v[84:87], s[64:65]
	global_store_dwordx4 v240, v[80:83], s[64:65] offset:16
	s_add_u32 s64, s16, 0x140000
	s_addc_u32 s65, s17, 0
	global_store_dwordx4 v240, v[76:79], s[64:65]
	global_store_dwordx4 v240, v[72:75], s[64:65] offset:16
	s_add_u32 s64, s16, 0x160000
	s_addc_u32 s65, s17, 0
	global_store_dwordx4 v240, v[68:71], s[64:65]
	global_store_dwordx4 v240, v[64:67], s[64:65] offset:16
	s_add_u32 s36, s16, 0x100000
	s_addc_u32 s37, s17, 0
	global_load_dwordx4 v[194:197], v240, s[36:37] offset:512
	global_load_dwordx4 v[198:201], v240, s[36:37] offset:528
	s_add_u32 s36, s16, 0x120000
	s_addc_u32 s37, s17, 0
	global_load_dwordx4 v[202:205], v240, s[36:37] offset:512
	global_load_dwordx4 v[208:211], v240, s[36:37] offset:528
	s_add_u32 s36, s16, 0x140000
	s_addc_u32 s37, s17, 0
	global_load_dwordx4 v[216:219], v240, s[36:37] offset:512
	global_load_dwordx4 v[220:223], v240, s[36:37] offset:528
	s_add_u32 s36, s16, 0x160000
	s_addc_u32 s37, s17, 0
	global_load_dwordx4 v[224:227], v240, s[36:37] offset:512
	global_load_dwordx4 v[228:231], v240, s[36:37] offset:528
	s_waitcnt vmcnt(16)
	v_fma_f32 v60, v124, v60, v128
	v_fma_f32 v61, v125, v61, v129
	v_fma_f32 v62, v126, v62, v130
	v_fma_f32 v63, v127, v63, v131
	v_fma_f32 v56, v120, v56, v132
	v_fma_f32 v57, v121, v57, v133
	v_fma_f32 v58, v122, v58, v134
	v_fma_f32 v59, v123, v59, v135
	v_fma_f32 v52, v124, v52, v136
	v_fma_f32 v53, v125, v53, v137
	v_fma_f32 v54, v126, v54, v138
	v_fma_f32 v55, v127, v55, v139
	v_fma_f32 v48, v120, v48, v170
	v_fma_f32 v49, v121, v49, v171
	v_fma_f32 v50, v122, v50, v172
	v_fma_f32 v51, v123, v51, v173
	v_fma_f32 v44, v124, v44, v174
	v_fma_f32 v45, v125, v45, v175
	v_fma_f32 v46, v126, v46, v176
	v_fma_f32 v47, v127, v47, v177
	v_fma_f32 v40, v120, v40, v178
	v_fma_f32 v41, v121, v41, v179
	v_fma_f32 v42, v122, v42, v180
	v_fma_f32 v43, v123, v43, v181
	v_fma_f32 v36, v124, v36, v182
	v_fma_f32 v37, v125, v37, v183
	v_fma_f32 v38, v126, v38, v184
	v_fma_f32 v39, v127, v39, v185
	v_fma_f32 v32, v120, v32, v190
	v_fma_f32 v33, v121, v33, v191
	v_fma_f32 v34, v122, v34, v192
	v_fma_f32 v35, v123, v35, v193
	global_store_dwordx4 v240, v[60:63], s[16:17] offset:512
	global_store_dwordx4 v240, v[56:59], s[16:17] offset:528
	s_add_u32 s64, s16, 0x20000
	s_addc_u32 s65, s17, 0
	global_store_dwordx4 v240, v[52:55], s[64:65] offset:512
	global_store_dwordx4 v240, v[48:51], s[64:65] offset:528
	s_add_u32 s64, s16, 0x40000
	s_addc_u32 s65, s17, 0
	global_store_dwordx4 v240, v[44:47], s[64:65] offset:512
	global_store_dwordx4 v240, v[40:43], s[64:65] offset:528
	s_add_u32 s64, s16, 0x60000
	s_addc_u32 s65, s17, 0
	global_store_dwordx4 v240, v[36:39], s[64:65] offset:512
	global_store_dwordx4 v240, v[32:35], s[64:65] offset:528
	s_waitcnt vmcnt(8)
	v_fma_f32 v28, v124, v28, v194
	v_fma_f32 v29, v125, v29, v195
	v_fma_f32 v30, v126, v30, v196
	v_fma_f32 v31, v127, v31, v197
	v_fma_f32 v24, v120, v24, v198
	v_fma_f32 v25, v121, v25, v199
	v_fma_f32 v26, v122, v26, v200
	v_fma_f32 v27, v123, v27, v201
	v_fma_f32 v20, v124, v20, v202
	v_fma_f32 v21, v125, v21, v203
	v_fma_f32 v22, v126, v22, v204
	v_fma_f32 v23, v127, v23, v205
	v_fma_f32 v16, v120, v16, v208
	v_fma_f32 v17, v121, v17, v209
	v_fma_f32 v18, v122, v18, v210
	v_fma_f32 v19, v123, v19, v211
	v_fma_f32 v12, v124, v12, v216
	v_fma_f32 v13, v125, v13, v217
	v_fma_f32 v14, v126, v14, v218
	v_fma_f32 v15, v127, v15, v219
	v_fma_f32 v8, v120, v8, v220
	v_fma_f32 v9, v121, v9, v221
	v_fma_f32 v10, v122, v10, v222
	v_fma_f32 v11, v123, v11, v223
	v_fma_f32 v4, v124, v4, v224
	v_fma_f32 v5, v125, v5, v225
	v_fma_f32 v6, v126, v6, v226
	v_fma_f32 v7, v127, v7, v227
	v_fma_f32 v0, v120, v0, v228
	v_fma_f32 v1, v121, v1, v229
	v_fma_f32 v2, v122, v2, v230
	v_fma_f32 v3, v123, v3, v231
	s_add_u32 s64, s16, 0x100000
	s_addc_u32 s65, s17, 0
	global_store_dwordx4 v240, v[28:31], s[64:65] offset:512
	global_store_dwordx4 v240, v[24:27], s[64:65] offset:528
	s_add_u32 s64, s16, 0x120000
	s_addc_u32 s65, s17, 0
	global_store_dwordx4 v240, v[20:23], s[64:65] offset:512
	global_store_dwordx4 v240, v[16:19], s[64:65] offset:528
	s_add_u32 s64, s16, 0x140000
	s_addc_u32 s65, s17, 0
	global_store_dwordx4 v240, v[12:15], s[64:65] offset:512
	global_store_dwordx4 v240, v[8:11], s[64:65] offset:528
	s_add_u32 s64, s16, 0x160000
	s_addc_u32 s65, s17, 0
	global_store_dwordx4 v240, v[4:7], s[64:65] offset:512
	global_store_dwordx4 v240, v[0:3], s[64:65] offset:528
	s_movk_i32 s94, 0xff00
	s_branch .Lmy_r1_end

; #define PG8_WAIT_V(n) asm volatile("s_waitcnt vmcnt(" #n ")" ::: "memory")
; #define PG8_BAR __builtin_amdgcn_s_barrier()
; template <class Epi, bool HAS_MID>
; __device__ __forceinline__ void gemm_phase(LAS unsigned char* lds, const Gemm g, const Sched& S, const Epi& E) {
;     ...
;         if (wr == 0) PG8_BAR;
;         E(acc, cur, wr, wc, fr, fq);
;         if (!has_next) break;
; #pragma unroll
;         for (int a = 0; a < 2; ++a)
; #pragma unroll
;             for (int b = 0; b < 2; ++b)
; #pragma unroll
;                 for (int m = 0; m < 4; ++m)
; #pragma unroll
;                     for (int n = 0; n < 2; ++n) acc[a][b][m][n] = (f32x4){0.f, 0.f, 0.f, 0.f};
;         cur = nxt; cA = nA; cB = nB; ++ui;
;         if (wr == 1) PG8_BAR;
;     }
;     PG8_WAIT_V(0);
;     PG8_BAR;
.LBB0_3039:
	v_lshl_add_u64 v[0:1], v[170:171], 2, v[36:37]
	global_store_dwordx4 v[0:1], v[32:35], off offset:528
.Lmy_r1_end:
	s_and_b64 vcc, exec, s[2:3]
	s_mov_b64 s[2:3], -1
	s_cbranch_vccnz .LBB0_3004
	s_andn2_b64 vcc, exec, s[14:15]
	s_cbranch_vccnz .LBB0_3003
	s_barrier
	s_branch .LBB0_3003
.LBB0_3042:
	s_waitcnt vmcnt(0)
	s_movk_i32 s86, 0x180
	s_movk_i32 s37, 0x50
	s_movk_i32 s60, 0x140
	s_movk_i32 s61, 0x340
	s_movk_i32 s64, 0x380
	s_movk_i32 s65, 0x210
	s_mov_b64 s[82:83], 0x25800000
	v_readlane_b32 s87, v255, 9
	s_barrier
	s_andn2_b64 vcc, exec, s[66:67]
	s_cbranch_vccnz .LBB0_3385
	s_branch .LBB0_3045
